# merge epilogue gate loads marked nt (once-read stream, keep merged RMW tiles in L2)
# speedup vs baseline: 1.0028x; 1.0028x over previous
.LBB0_1020:
	s_lshl_b32 s13, s20, 8
	s_lshl_b32 s20, s5, 10
	v_mbcnt_lo_u32_b32 v16, -1, 0
	v_mbcnt_hi_u32_b32 v16, -1, v16
	s_lshl_b32 s4, s4, 8
	v_and_or_b32 v176, v16, 15, s45
	s_ashr_i32 s21, s20, 31
	v_ashrrev_i32_e32 v16, 1, v16
	v_add_u32_e32 v168, s13, v176
	s_or_b32 s4, s4, s46
	s_lshl_b64 s[20:21], s[20:21], 1
	v_and_b32_e32 v16, -8, v16
	s_add_u32 s20, s43, s20
	v_ashrrev_i32_e32 v169, 31, v168
	v_add_u32_e32 v166, s4, v16
	s_addc_u32 s21, s44, s21
	v_lshlrev_b64 v[16:17], 13, v[168:169]
	v_lshl_add_u64 v[16:17], s[20:21], 0, v[16:17]
	v_ashrrev_i32_e32 v167, 31, v166
	v_lshl_add_u64 v[16:17], v[166:167], 1, v[16:17]
	global_load_dwordx4 v[156:159], v[16:17], off nt
	v_lshlrev_b64 v[18:19], 11, v[168:169]
	s_cmp_lg_u32 s5, 0
	v_lshl_add_u64 v[18:19], s[8:9], 0, v[18:19]
	s_cselect_b64 s[22:23], -1, 0
	s_cmp_eq_u32 s5, 0
	v_lshl_add_u64 v[172:173], v[166:167], 1, v[18:19]
	s_cbranch_scc1 .LBB0_1022
	global_load_dwordx4 v[44:47], v[172:173], off
.LBB0_1022:
	global_load_dwordx4 v[152:155], v[16:17], off offset:256 nt
	v_cndmask_b32_e64 v16, 0, 1, s[22:23]
	v_cmp_ne_u32_e64 s[4:5], 1, v16
	s_andn2_b64 vcc, exec, s[22:23]
	v_mov_b64_e32 v[230:231], v[250:251]
	v_mov_b32_e32 v243, v249
	v_mov_b32_e32 v251, v248
	s_cbranch_vccnz .LBB0_1024
	global_load_dwordx4 v[32:35], v[172:173], off offset:256
.LBB0_1024:
	v_or_b32_e32 v18, 16, v168
	v_ashrrev_i32_e32 v19, 31, v18
	v_lshlrev_b64 v[16:17], 13, v[18:19]
	v_lshl_add_u64 v[16:17], s[20:21], 0, v[16:17]
	v_lshl_add_u64 v[16:17], v[166:167], 1, v[16:17]
	global_load_dwordx4 v[148:151], v[16:17], off nt
	v_lshlrev_b64 v[18:19], 11, v[18:19]
	v_lshl_add_u64 v[18:19], s[8:9], 0, v[18:19]
	s_and_b64 vcc, exec, s[4:5]
	v_lshl_add_u64 v[170:171], v[166:167], 1, v[18:19]
	v_mov_b32_e32 v249, 0x358637bd
	s_cbranch_vccnz .LBB0_1026
	global_load_dwordx4 v[24:27], v[170:171], off
.LBB0_1026:
	global_load_dwordx4 v[136:139], v[16:17], off offset:256 nt
	s_mov_b32 s59, 0
	s_mov_b32 s58, 0x20000
	v_lshl_add_u64 v[252:253], v[16:17], 0, s[58:59]
	global_load_dwordx4 v[180:183], v[252:253], off nt
	global_load_dwordx4 v[184:187], v[252:253], off offset:256 nt
	s_mov_b32 s58, 0x40000
	v_lshl_add_u64 v[244:245], v[16:17], 0, s[58:59]
	global_load_dwordx4 v[188:191], v[244:245], off nt
	global_load_dwordx4 v[192:195], v[244:245], off offset:256 nt
	s_mov_b32 s58, 0xe0000
	v_lshl_add_u64 v[246:247], v[16:17], 0, s[58:59]
	global_load_dwordx4 v[196:199], v[246:247], off nt
	global_load_dwordx4 v[200:203], v[246:247], off offset:256 nt
	s_mov_b32 s58, 0x100000
	v_lshl_add_u64 v[252:253], v[16:17], 0, s[58:59]
	global_load_dwordx4 v[204:207], v[252:253], off nt
	global_load_dwordx4 v[208:211], v[252:253], off offset:256 nt
	s_mov_b32 s58, 0x120000
	v_lshl_add_u64 v[244:245], v[16:17], 0, s[58:59]
	global_load_dwordx4 v[222:225], v[244:245], off nt
	global_load_dwordx4 v[226:229], v[244:245], off offset:256 nt
	s_mov_b32 s58, 0x140000
	v_lshl_add_u64 v[246:247], v[16:17], 0, s[58:59]
	global_load_dwordx4 v[234:237], v[246:247], off nt
	global_load_dwordx4 v[238:241], v[246:247], off offset:256 nt
	s_and_b64 vcc, exec, s[4:5]
	v_mov_b32_e32 v248, 0x260
	s_cbranch_vccnz .LBB0_1028
	global_load_dwordx4 v[16:19], v[170:171], off offset:256
